# v43 + sample-row pre stores write-through (no wbl2 before the GEMM); cache invalidate of every grid barrier and of sample LN issued at arrival so it overlaps the arrival atomics/spin
# speedup vs baseline: 1.0130x; 1.0130x over previous
; __device__ __forceinline__ unsigned xb_ld(unsigned* p)              { return __hip_atomic_load(p, __ATOMIC_RELAXED, __HIP_MEMORY_SCOPE_AGENT); }
; __device__ __forceinline__ void xcd_barrier_complete(unsigned* bar, unsigned x, unsigned& nloc, unsigned& nx) {
;     const unsigned G = gridDim.x * gridDim.y * gridDim.z;
;     unsigned sum, cnt, mine, sp = 0u;
;     for (;;) {
;         sum = 0u; cnt = 0u; mine = 0u;
; #pragma unroll
;         for (unsigned j = 0; j < 16; ++j) { const unsigned c = xb_ld(&bar[XB_XCNT(j)]); sum += c; cnt += (c > 0u) ? 1u : 0u; mine = (j == x) ? c : mine; }
; __device__ __forceinline__ void xcd_barrier(const XcdBarrier& b) {
;     asm volatile("s_waitcnt vmcnt(0)" ::: "memory");
;     __syncthreads();
;     if (threadIdx.x == 0) {
;         unsigned* bar = b.bar;
;         __builtin_amdgcn_s_waitcnt(0);
;         unsigned nloc = b.st[0], nx = b.st[1];
;         if (nloc == 0u) { xcd_barrier_complete(bar, b.x, nloc, nx); b.st[0] = nloc; b.st[1] = nx; }
.LBB0_178:
	s_waitcnt vmcnt(0)
	s_waitcnt vmcnt(0)
	s_barrier
	s_mov_b64 s[0:1], exec
	v_readlane_b32 s4, v252, 6
	v_readlane_b32 s5, v252, 7
	s_and_b64 s[4:5], s[0:1], s[4:5]
	s_mov_b64 exec, s[4:5]
	s_cbranch_execz .LBB0_236
	s_add_i32 s3, 0, 0x23fc0
	v_mov_b32_e32 v0, s3
	s_waitcnt vmcnt(0) expcnt(0) lgkmcnt(0)
	buffer_inv sc1
	ds_read_b32 v2, v0
	s_add_i32 s3, 0, 0x23fc4
	v_mov_b32_e32 v0, s3
	ds_read_b32 v0, v0
	s_waitcnt lgkmcnt(1)
	v_cmp_ne_u32_e32 vcc, 0, v2
	s_cbranch_vccnz .LBB0_200
	s_add_u32 s4, s82, 0x38a00200
	s_addc_u32 s5, s83, 0
	s_add_u32 s6, s82, 0x38a00400
	s_addc_u32 s7, s83, 0
	s_add_u32 s8, s82, 0x38a00500
	s_addc_u32 s9, s83, 0
	s_add_u32 s10, s82, 0x38a00600
	s_addc_u32 s11, s83, 0
	s_add_u32 s14, s82, 0x38a00700
	s_addc_u32 s15, s83, 0
	s_add_u32 s16, s82, 0x38a00800
	s_addc_u32 s17, s83, 0
	s_add_u32 s18, s82, 0x38a00900
	s_addc_u32 s19, s83, 0
	s_add_u32 s20, s82, 0x38a00a00
	s_addc_u32 s21, s83, 0
	s_add_u32 s22, s82, 0x38a00b00
	s_addc_u32 s23, s83, 0
	s_add_u32 s24, s82, 0x38a00c00
	s_addc_u32 s25, s83, 0
	s_add_u32 s26, s82, 0x38a00d00
	s_addc_u32 s27, s83, 0
	s_add_u32 s28, s82, 0x38a00e00
	s_addc_u32 s29, s83, 0
	s_add_u32 s30, s82, 0x38a00f00
	s_addc_u32 s31, s83, 0
	s_add_u32 s34, s82, 0x38a01000
	s_addc_u32 s35, s83, 0
	s_add_u32 s36, s82, 0x38a01100
	s_addc_u32 s37, s83, 0
	s_add_u32 s38, s82, 0x38a01200
	v_readlane_b32 s3, v252, 0
	s_addc_u32 s39, s83, 0
	s_mul_i32 s3, s93, s3
	s_add_u32 s42, s82, 0x38a01300
	s_mul_i32 s3, s3, s92
	s_addc_u32 s43, s83, 0
	s_mov_b32 s33, 1
	v_mov_b32_e32 v16, 0
	s_branch .LBB0_182

; __device__ __forceinline__ unsigned xb_ld(unsigned* p)              { return __hip_atomic_load(p, __ATOMIC_RELAXED, __HIP_MEMORY_SCOPE_AGENT); }
; #define XB_SPIN(cond, bar) do { unsigned _sp = 0; while (cond) { __builtin_amdgcn_s_sleep(1); \
;     if ((++_sp & 255u) == 0u) { if (xb_ld(&(bar)[XB_TMO])) break; if (_sp > XB_SPIN_CAP) { atomicAdd(&(bar)[XB_TMO], 1u); break; } } } } while (0)
; __device__ __forceinline__ void xcd_barrier(const XcdBarrier& b) {
;     ...
;         } else {
;             XB_SPIN(xb_ld(&bar[XB_XGEN(b.x)]) == gen, bar);
;             __builtin_amdgcn_fence(__ATOMIC_ACQUIRE, "agent");
;             asm volatile("s_waitcnt vmcnt(0)" ::: "memory");
.LBB0_215:
	s_or_b64 exec, exec, s[8:9]
	s_waitcnt vmcnt(0)
	s_nop 0
	s_waitcnt vmcnt(0)

; __device__ __forceinline__ unsigned xb_ld(unsigned* p)              { return __hip_atomic_load(p, __ATOMIC_RELAXED, __HIP_MEMORY_SCOPE_AGENT); }
; __device__ __forceinline__ unsigned xb_add(unsigned* p, unsigned v) { return __hip_atomic_fetch_add(p, v, __ATOMIC_RELAXED, __HIP_MEMORY_SCOPE_AGENT); }
; #define XB_SPIN(cond, bar) do { unsigned _sp = 0; while (cond) { __builtin_amdgcn_s_sleep(1); \
;     if ((++_sp & 255u) == 0u) { if (xb_ld(&(bar)[XB_TMO])) break; if (_sp > XB_SPIN_CAP) { atomicAdd(&(bar)[XB_TMO], 1u); break; } } } } while (0)
; __device__ __forceinline__ void xcd_barrier(const XcdBarrier& b) {
;     ...
;             else XB_SPIN(xb_ld(&bar[XB_TOPGEN]) == tg, bar);
;             __builtin_amdgcn_fence(__ATOMIC_ACQUIRE, "agent");
;             xb_add(&bar[XB_XGEN(b.x)], 1u);
.LBB0_233:
	s_or_b64 exec, exec, s[6:7]
	s_mov_b64 s[6:7], exec
	v_mbcnt_lo_u32_b32 v0, s6, 0
	v_mbcnt_hi_u32_b32 v0, s7, v0
	v_cmp_eq_u32_e32 vcc, 0, v0
	s_waitcnt vmcnt(0)
	s_nop 0
	s_and_saveexec_b64 s[8:9], vcc
	s_cbranch_execz .LBB0_235
	s_bcnt1_i32_b64 s3, s[6:7]
	v_mov_b32_e32 v0, 0x2000
	v_mov_b32_e32 v1, s3
	global_atomic_add v0, v1, s[4:5] offset:1024

; __device__ __forceinline__ unsigned xb_ld(unsigned* p)              { return __hip_atomic_load(p, __ATOMIC_RELAXED, __HIP_MEMORY_SCOPE_AGENT); }
; __device__ __forceinline__ void xcd_barrier_complete(unsigned* bar, unsigned x, unsigned& nloc, unsigned& nx) {
;     const unsigned G = gridDim.x * gridDim.y * gridDim.z;
;     unsigned sum, cnt, mine, sp = 0u;
;     for (;;) {
;         sum = 0u; cnt = 0u; mine = 0u;
; #pragma unroll
;         for (unsigned j = 0; j < 16; ++j) { const unsigned c = xb_ld(&bar[XB_XCNT(j)]); sum += c; cnt += (c > 0u) ? 1u : 0u; mine = (j == x) ? c : mine; }
; __device__ __forceinline__ void xcd_barrier(const XcdBarrier& b) {
;     asm volatile("s_waitcnt vmcnt(0)" ::: "memory");
;     __syncthreads();
;     if (threadIdx.x == 0) {
;         unsigned* bar = b.bar;
;         __builtin_amdgcn_s_waitcnt(0);
;         unsigned nloc = b.st[0], nx = b.st[1];
;         if (nloc == 0u) { xcd_barrier_complete(bar, b.x, nloc, nx); b.st[0] = nloc; b.st[1] = nx; }
.LBB0_279:
	s_waitcnt vmcnt(0)
	s_barrier
	s_mov_b64 s[0:1], exec
	v_readlane_b32 s4, v252, 6
	v_readlane_b32 s5, v252, 7
	s_and_b64 s[4:5], s[0:1], s[4:5]
	s_mov_b64 exec, s[4:5]
	s_cbranch_execz .LBB0_331
	s_add_i32 s3, 0, 0x23fc0
	v_mov_b32_e32 v0, s3
	s_waitcnt vmcnt(0) expcnt(0) lgkmcnt(0)
	buffer_inv sc1
	ds_read_b32 v2, v0
	s_add_i32 s3, 0, 0x23fc4
	v_mov_b32_e32 v0, s3
	ds_read_b32 v0, v0
	s_waitcnt lgkmcnt(1)
	v_cmp_ne_u32_e32 vcc, 0, v2
	s_cbranch_vccnz .LBB0_295
	s_add_u32 s4, s82, 0x38a00200
	s_addc_u32 s5, s83, 0
	s_add_u32 s6, s82, 0x38a00400
	s_addc_u32 s7, s83, 0
	s_add_u32 s8, s82, 0x38a00500
	s_addc_u32 s9, s83, 0
	s_add_u32 s10, s82, 0x38a00600
	s_addc_u32 s11, s83, 0
	s_add_u32 s14, s82, 0x38a00700
	s_addc_u32 s15, s83, 0
	s_add_u32 s16, s82, 0x38a00800
	s_addc_u32 s17, s83, 0
	s_add_u32 s18, s82, 0x38a00900
	s_addc_u32 s19, s83, 0
	s_add_u32 s20, s82, 0x38a00a00
	s_addc_u32 s21, s83, 0
	s_add_u32 s22, s82, 0x38a00b00
	s_addc_u32 s23, s83, 0
	s_add_u32 s24, s82, 0x38a00c00
	s_addc_u32 s25, s83, 0
	s_add_u32 s26, s82, 0x38a00d00
	s_addc_u32 s27, s83, 0
	s_add_u32 s28, s82, 0x38a00e00
	s_addc_u32 s29, s83, 0
	s_add_u32 s30, s82, 0x38a00f00
	s_addc_u32 s31, s83, 0
	s_add_u32 s34, s82, 0x38a01000
	s_addc_u32 s35, s83, 0
	s_add_u32 s36, s82, 0x38a01100
	s_addc_u32 s37, s83, 0
	s_add_u32 s38, s82, 0x38a01200
	v_readlane_b32 s3, v252, 0
	s_addc_u32 s39, s83, 0
	s_mul_i32 s3, s93, s3
	s_add_u32 s42, s82, 0x38a01300
	s_mul_i32 s3, s3, s92
	s_addc_u32 s43, s83, 0
	s_mov_b32 s33, 1
	v_mov_b32_e32 v16, 0
	s_branch .LBB0_283

; __device__ __forceinline__ unsigned xb_ld(unsigned* p)              { return __hip_atomic_load(p, __ATOMIC_RELAXED, __HIP_MEMORY_SCOPE_AGENT); }
; __device__ __forceinline__ void xcd_barrier_complete(unsigned* bar, unsigned x, unsigned& nloc, unsigned& nx) {
;     const unsigned G = gridDim.x * gridDim.y * gridDim.z;
;     unsigned sum, cnt, mine, sp = 0u;
;     for (;;) {
;         sum = 0u; cnt = 0u; mine = 0u;
; #pragma unroll
;         for (unsigned j = 0; j < 16; ++j) { const unsigned c = xb_ld(&bar[XB_XCNT(j)]); sum += c; cnt += (c > 0u) ? 1u : 0u; mine = (j == x) ? c : mine; }
; __device__ __forceinline__ void xcd_barrier(const XcdBarrier& b) {
;     asm volatile("s_waitcnt vmcnt(0)" ::: "memory");
;     __syncthreads();
;     if (threadIdx.x == 0) {
;         unsigned* bar = b.bar;
;         __builtin_amdgcn_s_waitcnt(0);
;         unsigned nloc = b.st[0], nx = b.st[1];
;         if (nloc == 0u) { xcd_barrier_complete(bar, b.x, nloc, nx); b.st[0] = nloc; b.st[1] = nx; }
.LBB0_413:
	s_waitcnt vmcnt(0)
	s_barrier
	s_mov_b64 s[0:1], exec
	v_readlane_b32 s4, v252, 6
	v_readlane_b32 s5, v252, 7
	s_and_b64 s[4:5], s[0:1], s[4:5]
	s_mov_b64 exec, s[4:5]
	s_cbranch_execz .LBB0_465
	s_add_i32 s3, 0, 0x23fc0
	v_mov_b32_e32 v0, s3
	s_waitcnt vmcnt(0) expcnt(0) lgkmcnt(0)
	buffer_inv sc1
	ds_read_b32 v2, v0
	s_add_i32 s3, 0, 0x23fc4
	v_mov_b32_e32 v0, s3
	ds_read_b32 v0, v0
	s_waitcnt lgkmcnt(1)
	v_cmp_ne_u32_e32 vcc, 0, v2
	s_cbranch_vccnz .LBB0_429
	s_add_u32 s4, s82, 0x38a00200
	s_addc_u32 s5, s83, 0
	s_add_u32 s8, s82, 0x38a00400
	s_addc_u32 s9, s83, 0
	s_add_u32 s10, s82, 0x38a00500
	s_addc_u32 s11, s83, 0
	s_add_u32 s12, s82, 0x38a00600
	s_addc_u32 s13, s83, 0
	s_add_u32 s14, s82, 0x38a00700
	s_addc_u32 s15, s83, 0
	s_add_u32 s16, s82, 0x38a00800
	s_addc_u32 s17, s83, 0
	s_add_u32 s18, s82, 0x38a00900
	s_addc_u32 s19, s83, 0
	s_add_u32 s20, s82, 0x38a00a00
	s_addc_u32 s21, s83, 0
	s_add_u32 s22, s82, 0x38a00b00
	s_addc_u32 s23, s83, 0
	s_add_u32 s24, s82, 0x38a00c00
	s_addc_u32 s25, s83, 0
	s_add_u32 s26, s82, 0x38a00d00
	s_addc_u32 s27, s83, 0
	s_add_u32 s28, s82, 0x38a00e00
	s_addc_u32 s29, s83, 0
	s_add_u32 s30, s82, 0x38a00f00
	s_addc_u32 s31, s83, 0
	s_add_u32 s34, s82, 0x38a01000
	s_addc_u32 s35, s83, 0
	s_add_u32 s36, s82, 0x38a01100
	s_addc_u32 s37, s83, 0
	s_add_u32 s38, s82, 0x38a01200
	v_readlane_b32 s3, v252, 0
	s_addc_u32 s39, s83, 0
	s_mul_i32 s3, s93, s3
	s_add_u32 s42, s82, 0x38a01300
	s_mul_i32 s3, s3, s92
	s_addc_u32 s43, s83, 0
	s_mov_b32 s33, 1
	v_mov_b32_e32 v16, 0
	s_branch .LBB0_417

; __device__ __forceinline__ unsigned xb_ld(unsigned* p)              { return __hip_atomic_load(p, __ATOMIC_RELAXED, __HIP_MEMORY_SCOPE_AGENT); }
; #define XB_SPIN(cond, bar) do { unsigned _sp = 0; while (cond) { __builtin_amdgcn_s_sleep(1); \
;     if ((++_sp & 255u) == 0u) { if (xb_ld(&(bar)[XB_TMO])) break; if (_sp > XB_SPIN_CAP) { atomicAdd(&(bar)[XB_TMO], 1u); break; } } } } while (0)
; __device__ __forceinline__ void xcd_barrier(const XcdBarrier& b) {
;     ...
;         } else {
;             XB_SPIN(xb_ld(&bar[XB_XGEN(b.x)]) == gen, bar);
;             __builtin_amdgcn_fence(__ATOMIC_ACQUIRE, "agent");
;             asm volatile("s_waitcnt vmcnt(0)" ::: "memory");
.LBB0_444:
	s_or_b64 exec, exec, s[10:11]
	s_waitcnt vmcnt(0)
	s_nop 0
	s_waitcnt vmcnt(0)

; __device__ __forceinline__ unsigned xb_ld(unsigned* p)              { return __hip_atomic_load(p, __ATOMIC_RELAXED, __HIP_MEMORY_SCOPE_AGENT); }
; __device__ __forceinline__ unsigned xb_add(unsigned* p, unsigned v) { return __hip_atomic_fetch_add(p, v, __ATOMIC_RELAXED, __HIP_MEMORY_SCOPE_AGENT); }
; #define XB_SPIN(cond, bar) do { unsigned _sp = 0; while (cond) { __builtin_amdgcn_s_sleep(1); \
;     if ((++_sp & 255u) == 0u) { if (xb_ld(&(bar)[XB_TMO])) break; if (_sp > XB_SPIN_CAP) { atomicAdd(&(bar)[XB_TMO], 1u); break; } } } } while (0)
; __device__ __forceinline__ void xcd_barrier(const XcdBarrier& b) {
;     ...
;             else XB_SPIN(xb_ld(&bar[XB_TOPGEN]) == tg, bar);
;             __builtin_amdgcn_fence(__ATOMIC_ACQUIRE, "agent");
;             xb_add(&bar[XB_XGEN(b.x)], 1u);
.LBB0_462:
	s_or_b64 exec, exec, s[8:9]
	s_mov_b64 s[8:9], exec
	v_mbcnt_lo_u32_b32 v0, s8, 0
	v_mbcnt_hi_u32_b32 v0, s9, v0
	v_cmp_eq_u32_e32 vcc, 0, v0
	s_waitcnt vmcnt(0)
	s_nop 0
	s_and_saveexec_b64 s[10:11], vcc
	s_cbranch_execz .LBB0_464
	s_bcnt1_i32_b64 s3, s[8:9]
	v_mov_b32_e32 v0, 0x2000
	v_mov_b32_e32 v1, s3
	global_atomic_add v0, v1, s[4:5] offset:1024

; __device__ __forceinline__ unsigned xb_ld(unsigned* p)              { return __hip_atomic_load(p, __ATOMIC_RELAXED, __HIP_MEMORY_SCOPE_AGENT); }
; __device__ __forceinline__ void xcd_barrier_complete(unsigned* bar, unsigned x, unsigned& nloc, unsigned& nx) {
;     const unsigned G = gridDim.x * gridDim.y * gridDim.z;
;     unsigned sum, cnt, mine, sp = 0u;
;     for (;;) {
;         sum = 0u; cnt = 0u; mine = 0u;
; #pragma unroll
;         for (unsigned j = 0; j < 16; ++j) { const unsigned c = xb_ld(&bar[XB_XCNT(j)]); sum += c; cnt += (c > 0u) ? 1u : 0u; mine = (j == x) ? c : mine; }
; __device__ __forceinline__ void xcd_barrier(const XcdBarrier& b) {
;     asm volatile("s_waitcnt vmcnt(0)" ::: "memory");
;     __syncthreads();
;     if (threadIdx.x == 0) {
;         unsigned* bar = b.bar;
;         __builtin_amdgcn_s_waitcnt(0);
;         unsigned nloc = b.st[0], nx = b.st[1];
;         if (nloc == 0u) { xcd_barrier_complete(bar, b.x, nloc, nx); b.st[0] = nloc; b.st[1] = nx; }
.LBB0_470:
	s_or_b64 exec, exec, s[0:1]
	s_waitcnt vmcnt(0)
	s_barrier
	s_mov_b64 s[0:1], exec
	v_readlane_b32 s4, v252, 6
	v_readlane_b32 s5, v252, 7
	s_and_b64 s[4:5], s[0:1], s[4:5]
	s_mov_b64 exec, s[4:5]
	s_cbranch_execz .LBB0_522
	s_add_i32 s3, 0, 0x23fc0
	v_mov_b32_e32 v0, s3
	s_waitcnt vmcnt(0) expcnt(0) lgkmcnt(0)
	buffer_inv sc1
	ds_read_b32 v2, v0
	s_add_i32 s3, 0, 0x23fc4
	v_mov_b32_e32 v0, s3
	ds_read_b32 v0, v0
	s_waitcnt lgkmcnt(1)
	v_cmp_ne_u32_e32 vcc, 0, v2
	s_cbranch_vccnz .LBB0_486
	s_add_u32 s4, s82, 0x38a00200
	s_addc_u32 s5, s83, 0
	s_add_u32 s8, s82, 0x38a00400
	s_addc_u32 s9, s83, 0
	s_add_u32 s10, s82, 0x38a00500
	s_addc_u32 s11, s83, 0
	s_add_u32 s12, s82, 0x38a00600
	s_addc_u32 s13, s83, 0
	s_add_u32 s14, s82, 0x38a00700
	s_addc_u32 s15, s83, 0
	s_add_u32 s16, s82, 0x38a00800
	s_addc_u32 s17, s83, 0
	s_add_u32 s18, s82, 0x38a00900
	s_addc_u32 s19, s83, 0
	s_add_u32 s20, s82, 0x38a00a00
	s_addc_u32 s21, s83, 0
	s_add_u32 s22, s82, 0x38a00b00
	s_addc_u32 s23, s83, 0
	s_add_u32 s24, s82, 0x38a00c00
	s_addc_u32 s25, s83, 0
	s_add_u32 s26, s82, 0x38a00d00
	s_addc_u32 s27, s83, 0
	s_add_u32 s28, s82, 0x38a00e00
	s_addc_u32 s29, s83, 0
	s_add_u32 s30, s82, 0x38a00f00
	s_addc_u32 s31, s83, 0
	s_add_u32 s34, s82, 0x38a01000
	s_addc_u32 s35, s83, 0
	s_add_u32 s36, s82, 0x38a01100
	s_addc_u32 s37, s83, 0
	s_add_u32 s38, s82, 0x38a01200
	v_readlane_b32 s3, v252, 0
	s_addc_u32 s39, s83, 0
	s_mul_i32 s3, s93, s3
	s_add_u32 s40, s82, 0x38a01300
	s_mul_i32 s3, s3, s92
	s_addc_u32 s41, s83, 0
	s_mov_b32 s33, 1
	v_mov_b32_e32 v16, 0
	s_branch .LBB0_474

; __device__ __forceinline__ unsigned xb_ld(unsigned* p)              { return __hip_atomic_load(p, __ATOMIC_RELAXED, __HIP_MEMORY_SCOPE_AGENT); }
; __device__ __forceinline__ void xcd_barrier_complete(unsigned* bar, unsigned x, unsigned& nloc, unsigned& nx) {
;     const unsigned G = gridDim.x * gridDim.y * gridDim.z;
;     unsigned sum, cnt, mine, sp = 0u;
;     for (;;) {
;         sum = 0u; cnt = 0u; mine = 0u;
; #pragma unroll
;         for (unsigned j = 0; j < 16; ++j) { const unsigned c = xb_ld(&bar[XB_XCNT(j)]); sum += c; cnt += (c > 0u) ? 1u : 0u; mine = (j == x) ? c : mine; }
; __device__ __forceinline__ void xcd_barrier(const XcdBarrier& b) {
;     asm volatile("s_waitcnt vmcnt(0)" ::: "memory");
;     __syncthreads();
;     if (threadIdx.x == 0) {
;         unsigned* bar = b.bar;
;         __builtin_amdgcn_s_waitcnt(0);
;         unsigned nloc = b.st[0], nx = b.st[1];
;         if (nloc == 0u) { xcd_barrier_complete(bar, b.x, nloc, nx); b.st[0] = nloc; b.st[1] = nx; }
.LBB0_549:
	s_waitcnt vmcnt(0)
	s_barrier
	s_mov_b64 s[0:1], exec
	v_readlane_b32 s4, v252, 6
	v_readlane_b32 s5, v252, 7
	v_readlane_b32 s66, v252, 10
	s_and_b64 s[4:5], s[0:1], s[4:5]
	v_readlane_b32 s67, v252, 11
	s_mov_b64 exec, s[4:5]
	s_cbranch_execz .LBB0_601
	s_add_i32 s3, 0, 0x23fc0
	v_mov_b32_e32 v0, s3
	s_waitcnt vmcnt(0) expcnt(0) lgkmcnt(0)
	buffer_inv sc1
	ds_read_b32 v2, v0
	s_add_i32 s3, 0, 0x23fc4
	v_mov_b32_e32 v0, s3
	ds_read_b32 v0, v0
	s_waitcnt lgkmcnt(1)
	v_cmp_ne_u32_e32 vcc, 0, v2
	s_cbranch_vccnz .LBB0_565
	s_add_u32 s4, s66, 0x38a00200
	s_addc_u32 s5, s67, 0
	s_add_u32 s6, s66, 0x38a00400
	s_addc_u32 s7, s67, 0
	s_add_u32 s8, s66, 0x38a00500
	s_addc_u32 s9, s67, 0
	s_add_u32 s10, s66, 0x38a00600
	s_addc_u32 s11, s67, 0
	s_add_u32 s12, s66, 0x38a00700
	s_addc_u32 s13, s67, 0
	s_add_u32 s14, s66, 0x38a00800
	s_addc_u32 s15, s67, 0
	s_add_u32 s16, s66, 0x38a00900
	s_addc_u32 s17, s67, 0
	s_add_u32 s18, s66, 0x38a00a00
	s_addc_u32 s19, s67, 0
	s_add_u32 s20, s66, 0x38a00b00
	s_addc_u32 s21, s67, 0
	s_add_u32 s22, s66, 0x38a00c00
	s_addc_u32 s23, s67, 0
	s_add_u32 s24, s66, 0x38a00d00
	s_addc_u32 s25, s67, 0
	s_add_u32 s26, s66, 0x38a00e00
	s_addc_u32 s27, s67, 0
	s_add_u32 s28, s66, 0x38a00f00
	s_addc_u32 s29, s67, 0
	s_add_u32 s30, s66, 0x38a01000
	s_addc_u32 s31, s67, 0
	s_add_u32 s34, s66, 0x38a01100
	s_addc_u32 s35, s67, 0
	s_add_u32 s36, s66, 0x38a01200
	v_readlane_b32 s3, v252, 0
	s_addc_u32 s37, s67, 0
	s_mul_i32 s3, s93, s3
	s_add_u32 s38, s66, 0x38a01300
	s_mul_i32 s3, s3, s92
	s_addc_u32 s39, s67, 0
	s_mov_b32 s33, 1
	v_mov_b32_e32 v16, 0
	s_branch .LBB0_553

; __device__ __forceinline__ unsigned xb_ld(unsigned* p)              { return __hip_atomic_load(p, __ATOMIC_RELAXED, __HIP_MEMORY_SCOPE_AGENT); }
; __device__ __forceinline__ void xcd_barrier_complete(unsigned* bar, unsigned x, unsigned& nloc, unsigned& nx) {
;     const unsigned G = gridDim.x * gridDim.y * gridDim.z;
;     unsigned sum, cnt, mine, sp = 0u;
;     for (;;) {
;         sum = 0u; cnt = 0u; mine = 0u;
; #pragma unroll
;         for (unsigned j = 0; j < 16; ++j) { const unsigned c = xb_ld(&bar[XB_XCNT(j)]); sum += c; cnt += (c > 0u) ? 1u : 0u; mine = (j == x) ? c : mine; }
; __device__ __forceinline__ void xcd_barrier(const XcdBarrier& b) {
;     asm volatile("s_waitcnt vmcnt(0)" ::: "memory");
;     __syncthreads();
;     if (threadIdx.x == 0) {
;         unsigned* bar = b.bar;
;         __builtin_amdgcn_s_waitcnt(0);
;         unsigned nloc = b.st[0], nx = b.st[1];
;         if (nloc == 0u) { xcd_barrier_complete(bar, b.x, nloc, nx); b.st[0] = nloc; b.st[1] = nx; }
.LBB0_608:
	s_or_b64 exec, exec, s[0:1]
	s_waitcnt vmcnt(0)
	s_barrier
	s_mov_b64 s[0:1], exec
	v_readlane_b32 s4, v252, 6
	v_readlane_b32 s5, v252, 7
	s_and_b64 s[4:5], s[0:1], s[4:5]
	s_mov_b64 exec, s[4:5]
	s_cbranch_execz .LBB0_660
	s_add_i32 s3, 0, 0x23fc0
	v_mov_b32_e32 v0, s3
	s_waitcnt vmcnt(0) expcnt(0) lgkmcnt(0)
	buffer_inv sc1
	ds_read_b32 v2, v0
	s_add_i32 s3, 0, 0x23fc4
	v_mov_b32_e32 v0, s3
	ds_read_b32 v0, v0
	s_waitcnt lgkmcnt(1)
	v_cmp_ne_u32_e32 vcc, 0, v2
	s_cbranch_vccnz .LBB0_624
	s_add_u32 s4, s66, 0x38a00200
	s_addc_u32 s5, s67, 0
	s_add_u32 s8, s66, 0x38a00400
	s_addc_u32 s9, s67, 0
	s_add_u32 s10, s66, 0x38a00500
	s_addc_u32 s11, s67, 0
	s_add_u32 s12, s66, 0x38a00600
	s_addc_u32 s13, s67, 0
	s_add_u32 s14, s66, 0x38a00700
	s_addc_u32 s15, s67, 0
	s_add_u32 s16, s66, 0x38a00800
	s_addc_u32 s17, s67, 0
	s_add_u32 s18, s66, 0x38a00900
	s_addc_u32 s19, s67, 0
	s_add_u32 s20, s66, 0x38a00a00
	s_addc_u32 s21, s67, 0
	s_add_u32 s22, s66, 0x38a00b00
	s_addc_u32 s23, s67, 0
	s_add_u32 s24, s66, 0x38a00c00
	s_addc_u32 s25, s67, 0
	s_add_u32 s26, s66, 0x38a00d00
	s_addc_u32 s27, s67, 0
	s_add_u32 s28, s66, 0x38a00e00
	s_addc_u32 s29, s67, 0
	s_add_u32 s30, s66, 0x38a00f00
	s_addc_u32 s31, s67, 0
	s_add_u32 s34, s66, 0x38a01000
	s_addc_u32 s35, s67, 0
	s_add_u32 s36, s66, 0x38a01100
	s_addc_u32 s37, s67, 0
	s_add_u32 s38, s66, 0x38a01200
	v_readlane_b32 s3, v252, 0
	s_addc_u32 s39, s67, 0
	s_mul_i32 s3, s93, s3
	s_add_u32 s40, s66, 0x38a01300
	s_mul_i32 s3, s3, s92
	s_addc_u32 s41, s67, 0
	s_mov_b32 s33, 1
	v_mov_b32_e32 v16, 0
	s_branch .LBB0_612

; #define MFMA16(a, b, c) __builtin_amdgcn_mfma_f32_16x16x32_bf16((a), (b), (c), 0, 0, 0)
; template <int K>
; __device__ __forceinline__ void skinny_sample_gemm(const bfu* __restrict__ A, const bfu* __restrict__ Bt, const float* __restrict__ res, float* __restrict__ pre, float* ldsf, int bid) {
;     const int tid = threadIdx.x, lane = tid & 63, wave = __builtin_amdgcn_readfirstlane(tid >> 6), l15 = lane & 15, quad = lane >> 4;
;     const int rg = bid >> 4, cg = bid & 15;
;     constexpr int KW = K / 8, NS = KW / 32;
;     const bfu* ap = A + (size_t)(MP + rg * 16 + l15) * K + wave * KW + quad * 8;
;     const bfu* bp = Bt + (size_t)(cg * 64 + l15) * K + wave * KW + quad * 8;
;     f32x4 acc[4];
; #pragma unroll
;     for (int nt = 0; nt < 4; ++nt) acc[nt] = (f32x4){0.f, 0.f, 0.f, 0.f};
; #pragma unroll
;     for (int ks = 0; ks < NS; ++ks) {
;         const bf16x8 af = ld8g(ap + ks * 32);
; #pragma unroll
;         for (int nt = 0; nt < 4; ++nt) acc[nt] = MFMA16(af, ld8g(bp + (size_t)nt * 16 * K + ks * 32), acc[nt]);
;     }
.LBB0_1022:
	s_and_b64 vcc, exec, s[0:1]
	s_cbranch_vccz .LBB0_1296
	s_add_u32 s3, s66, 0x38a0c000
	s_addc_u32 s33, s67, 0
	s_add_u32 s22, s66, 0x24c00000
	s_addc_u32 s23, s67, 0
	s_add_u32 s24, s66, 0xd00000
	s_addc_u32 s25, s67, 0
	s_add_u32 s12, s66, 0x28d00000
	v_readfirstlane_b32 s4, v172
	s_addc_u32 s13, s67, 0
	s_lshr_b32 s5, s4, 6
	s_and_b32 s4, s2, -16
	s_add_i32 s6, s4, 0x4000
	v_or_b32_e32 v134, s6, v174
	s_lshl_b32 s6, s2, 6
	s_and_b32 s6, s6, 0x3c0
	v_or_b32_e32 v187, s6, v174
	v_ashrrev_i32_e32 v135, 31, v134
	v_mov_b32_e32 v129, 0
	v_lshlrev_b32_e32 v128, 12, v187
	v_lshlrev_b64 v[0:1], 12, v[134:135]
	s_mov_b32 s11, 0
	v_lshl_add_u64 v[2:3], s[24:25], 0, v[128:129]
	s_lshl_b32 s10, s5, 9
	v_lshl_add_u64 v[2:3], v[2:3], 0, s[10:11]
	v_lshl_add_u64 v[0:1], s[22:23], 0, v[0:1]
	v_mov_b32_e32 v177, v129
	v_readlane_b32 s0, v252, 1
	v_lshl_add_u64 v[0:1], v[0:1], 0, s[10:11]
	v_lshl_add_u64 v[50:51], v[2:3], 0, v[176:177]
	s_mov_b32 s7, 0x10000
	v_readlane_b32 s1, v252, 2
	v_lshl_add_u64 v[48:49], v[0:1], 0, v[176:177]
	v_add_co_u32_e32 v52, vcc, s7, v50
	global_load_dwordx4 v[0:3], v[48:49], off
	global_load_dwordx4 v[4:7], v[50:51], off
	v_addc_co_u32_e32 v53, vcc, 0, v51, vcc
	s_mov_b32 s7, 0x20000
	v_add_co_u32_e32 v54, vcc, s7, v50
	s_mov_b32 s7, 0x30000
	s_nop 0
	v_addc_co_u32_e32 v55, vcc, 0, v51, vcc
	v_add_co_u32_e32 v56, vcc, s7, v50
	global_load_dwordx4 v[8:11], v[52:53], off
	global_load_dwordx4 v[12:15], v[54:55], off
	v_addc_co_u32_e32 v57, vcc, 0, v51, vcc
	global_load_dwordx4 v[16:19], v[56:57], off
	global_load_dwordx4 v[20:23], v[48:49], off offset:64
	global_load_dwordx4 v[24:27], v[50:51], off offset:64
	global_load_dwordx4 v[28:31], v[52:53], off offset:64
	s_waitcnt lgkmcnt(0)
	global_load_dwordx4 v[32:35], v[54:55], off offset:64
	global_load_dwordx4 v[36:39], v[56:57], off offset:64
	global_load_dwordx4 v[40:43], v[48:49], off offset:128
	global_load_dwordx4 v[44:47], v[50:51], off offset:128
	s_lshl_b32 s5, s5, 12
	v_lshlrev_b32_e32 v135, 10, v175
	v_lshlrev_b32_e32 v186, 2, v174
	s_add_i32 s5, s5, 0
	s_lshl_b32 s10, s6, 2
	v_lshlrev_b32_e32 v128, 2, v179
	s_waitcnt vmcnt(10)
	v_mfma_f32_16x16x32_bf16 v[4:7], v[0:3], v[4:7], 0
	s_waitcnt vmcnt(9)
	v_mfma_f32_16x16x32_bf16 v[8:11], v[0:3], v[8:11], 0
	s_waitcnt vmcnt(8)
	v_mfma_f32_16x16x32_bf16 v[12:15], v[0:3], v[12:15], 0
	s_waitcnt vmcnt(7)
	v_mfma_f32_16x16x32_bf16 v[0:3], v[0:3], v[16:19], 0
	global_load_dwordx4 v[16:19], v[52:53], off offset:128
	s_waitcnt vmcnt(6)
	v_mfma_f32_16x16x32_bf16 v[4:7], v[20:23], v[24:27], v[4:7]
	global_load_dwordx4 v[24:27], v[54:55], off offset:128
	s_waitcnt vmcnt(6)
	v_mfma_f32_16x16x32_bf16 v[8:11], v[20:23], v[28:31], v[8:11]
	global_load_dwordx4 v[28:31], v[56:57], off offset:128
	s_waitcnt vmcnt(6)
	v_mfma_f32_16x16x32_bf16 v[12:15], v[20:23], v[32:35], v[12:15]
	global_load_dwordx4 v[32:35], v[48:49], off offset:192
	s_waitcnt vmcnt(6)
	v_mfma_f32_16x16x32_bf16 v[0:3], v[20:23], v[36:39], v[0:3]
	global_load_dwordx4 v[20:23], v[50:51], off offset:192
	global_load_dwordx4 v[36:39], v[52:53], off offset:192
	s_waitcnt vmcnt(6)
	v_mfma_f32_16x16x32_bf16 v[4:7], v[40:43], v[44:47], v[4:7]
	s_waitcnt vmcnt(5)
	v_mfma_f32_16x16x32_bf16 v[8:11], v[40:43], v[16:19], v[8:11]
	global_load_dwordx4 v[16:19], v[54:55], off offset:192
	global_load_dwordx4 v[44:47], v[56:57], off offset:192
	s_waitcnt vmcnt(6)
	v_mfma_f32_16x16x32_bf16 v[12:15], v[40:43], v[24:27], v[12:15]
	global_load_dwordx4 v[24:27], v[48:49], off offset:256
	s_waitcnt vmcnt(6)
	v_mfma_f32_16x16x32_bf16 v[0:3], v[40:43], v[28:31], v[0:3]
	global_load_dwordx4 v[28:31], v[50:51], off offset:256
	s_waitcnt vmcnt(5)
	v_mfma_f32_16x16x32_bf16 v[4:7], v[32:35], v[20:23], v[4:7]
	global_load_dwordx4 v[20:23], v[52:53], off offset:256
	s_waitcnt vmcnt(5)
	v_mfma_f32_16x16x32_bf16 v[8:11], v[32:35], v[36:39], v[8:11]
	global_load_dwordx4 v[36:39], v[54:55], off offset:256
	global_load_dwordx4 v[40:43], v[56:57], off offset:256
	s_waitcnt vmcnt(6)
	v_mfma_f32_16x16x32_bf16 v[12:15], v[32:35], v[16:19], v[12:15]
	global_load_dwordx4 v[16:19], v[48:49], off offset:320
	s_waitcnt vmcnt(6)
	v_mfma_f32_16x16x32_bf16 v[0:3], v[32:35], v[44:47], v[0:3]
	global_load_dwordx4 v[32:35], v[50:51], off offset:320
	s_waitcnt vmcnt(5)
	v_mfma_f32_16x16x32_bf16 v[4:7], v[24:27], v[28:31], v[4:7]
	global_load_dwordx4 v[28:31], v[52:53], off offset:320
	s_waitcnt vmcnt(5)
	v_mfma_f32_16x16x32_bf16 v[8:11], v[24:27], v[20:23], v[8:11]
	global_load_dwordx4 v[20:23], v[54:55], off offset:320
	global_load_dwordx4 v[44:47], v[56:57], off offset:320
	s_waitcnt vmcnt(6)
	v_mfma_f32_16x16x32_bf16 v[12:15], v[24:27], v[36:39], v[12:15]
	global_load_dwordx4 v[36:39], v[48:49], off offset:384
	s_waitcnt vmcnt(6)
	v_mfma_f32_16x16x32_bf16 v[0:3], v[24:27], v[40:43], v[0:3]
	global_load_dwordx4 v[24:27], v[50:51], off offset:384
	s_waitcnt vmcnt(5)
; __device__ __forceinline__ unsigned xb_add(unsigned* p, unsigned v) { return __hip_atomic_fetch_add(p, v, __ATOMIC_RELAXED, __HIP_MEMORY_SCOPE_AGENT); }
; template <int K>
; __device__ __forceinline__ void skinny_sample_gemm(const bfu* __restrict__ A, const bfu* __restrict__ Bt, const float* __restrict__ res, float* __restrict__ pre, float* ldsf, int bid) {
;     ...
;     __syncthreads();
; #pragma unroll
;     for (int i = 0; i < 2; ++i) {
;         const int e = tid + 512 * i, r = e >> 6, c = e & 63;
;         float v = 0.f;
; #pragma unroll
;         for (int w = 0; w < 8; ++w) v += ldsf[w * 1024 + e];
;         const size_t row = (size_t)(rg * 16 + r);
;         pre[(MP + row) * 1024 + cg * 64 + c] = v + ALPHA * res[row * 1024 + cg * 64 + c];
;     }
;     __syncthreads();
; }
; __device__ __forceinline__ void sample_rows_publish(unsigned* cnt_s, int bid) {
;     asm volatile("s_waitcnt vmcnt(0)" ::: "memory");
;     __syncthreads();
;     if (threadIdx.x == 0) { __builtin_amdgcn_fence(__ATOMIC_RELEASE, "agent"); asm volatile("s_waitcnt vmcnt(0)" ::: "memory"); xb_add(cnt_s + (bid >> 4) * 64, 1u); }
; }
	v_mfma_f32_16x16x32_bf16 v[4:7], v[16:19], v[32:35], v[4:7]
	global_load_dwordx4 v[32:35], v[52:53], off offset:384
	s_waitcnt vmcnt(5)
	v_mfma_f32_16x16x32_bf16 v[8:11], v[16:19], v[28:31], v[8:11]
	global_load_dwordx4 v[28:31], v[54:55], off offset:384
	global_load_dwordx4 v[40:43], v[56:57], off offset:384
	s_load_dwordx2 s[0:1], s[0:1], 0x8
	s_waitcnt lgkmcnt(0)
	s_add_u32 s0, s0, s10
	s_waitcnt vmcnt(6)
	v_mfma_f32_16x16x32_bf16 v[12:15], v[16:19], v[20:23], v[12:15]
	global_load_dwordx4 v[20:23], v[48:49], off offset:448
	s_addc_u32 s1, s1, 0
	s_waitcnt vmcnt(6)
	v_mfma_f32_16x16x32_bf16 v[0:3], v[16:19], v[44:47], v[0:3]
	global_load_dwordx4 v[16:19], v[50:51], off offset:448
	s_waitcnt vmcnt(5)
	v_mfma_f32_16x16x32_bf16 v[4:7], v[36:39], v[24:27], v[4:7]
	global_load_dwordx4 v[24:27], v[52:53], off offset:448
	s_waitcnt vmcnt(5)
	v_mfma_f32_16x16x32_bf16 v[8:11], v[36:39], v[32:35], v[8:11]
	global_load_dwordx4 v[32:35], v[54:55], off offset:448
	s_waitcnt vmcnt(5)
	v_mfma_f32_16x16x32_bf16 v[12:15], v[36:39], v[28:31], v[12:15]
	global_load_dwordx4 v[28:31], v[56:57], off offset:448
	s_waitcnt vmcnt(5)
	v_mfma_f32_16x16x32_bf16 v[0:3], v[36:39], v[40:43], v[0:3]
	s_waitcnt vmcnt(3)
	v_mfma_f32_16x16x32_bf16 v[4:7], v[20:23], v[16:19], v[4:7]
	v_add3_u32 v16, s5, v135, v186
	s_waitcnt vmcnt(2)
	v_mfma_f32_16x16x32_bf16 v[8:11], v[20:23], v[24:27], v[8:11]
	s_waitcnt vmcnt(1)
	v_mfma_f32_16x16x32_bf16 v[12:15], v[20:23], v[32:35], v[12:15]
	s_waitcnt vmcnt(0)
	v_mfma_f32_16x16x32_bf16 v[0:3], v[20:23], v[28:31], v[0:3]
	s_nop 3
	ds_write2_b32 v16, v4, v8 offset1:16
	ds_write2_b32 v16, v5, v9 offset0:64 offset1:80
	ds_write2_b32 v16, v6, v10 offset0:128 offset1:144
	ds_write2_b32 v16, v7, v11 offset0:192 offset1:208
	ds_write2_b32 v16, v12, v0 offset0:32 offset1:48
	ds_write2_b32 v16, v13, v1 offset0:96 offset1:112
	ds_write2_b32 v16, v14, v2 offset0:160 offset1:176
	ds_write2_b32 v16, v15, v3 offset0:224 offset1:240
	v_add_u32_e32 v4, 0x200, v172
	v_or_b32_e32 v2, s4, v194
	v_lshrrev_b32_e32 v4, 6, v4
	v_ashrrev_i32_e32 v3, 31, v2
	v_add_u32_e32 v4, s4, v4
	v_lshl_add_u64 v[0:1], s[0:1], 0, v[128:129]
	v_lshlrev_b64 v[130:131], 12, v[2:3]
	v_ashrrev_i32_e32 v5, 31, v4
	v_lshl_add_u64 v[2:3], v[0:1], 0, v[130:131]
	v_lshlrev_b64 v[132:133], 12, v[4:5]
	s_waitcnt lgkmcnt(0)
	s_barrier
	v_lshl_add_u64 v[0:1], v[0:1], 0, v[132:133]
	global_load_dword v20, v[2:3], off
	global_load_dword v21, v[0:1], off
	ds_read2st64_b32 v[4:5], v173 offset1:8
	ds_read2st64_b32 v[6:7], v173 offset0:16 offset1:24
	ds_read2st64_b32 v[8:9], v173 offset0:32 offset1:40
	ds_read2st64_b32 v[10:11], v173 offset0:48 offset1:56
	ds_read2st64_b32 v[12:13], v173 offset0:64 offset1:72
	ds_read2st64_b32 v[14:15], v173 offset0:80 offset1:88
	ds_read2st64_b32 v[16:17], v173 offset0:96 offset1:104
	ds_read2st64_b32 v[18:19], v173 offset0:112 offset1:120
	s_waitcnt lgkmcnt(7)
	v_add_f32_e32 v4, 0, v4
	v_add_f32_e32 v5, 0, v5
	s_waitcnt lgkmcnt(6)
	v_add_f32_e32 v4, v4, v6
	v_add_f32_e32 v5, v5, v7
	s_waitcnt lgkmcnt(5)
	v_add_f32_e32 v4, v4, v8
	v_lshl_add_u64 v[0:1], s[12:13], 0, v[130:131]
	v_add_f32_e32 v5, v5, v9
	s_waitcnt lgkmcnt(4)
	v_add_f32_e32 v4, v4, v10
	v_lshl_add_u64 v[0:1], v[0:1], 0, s[10:11]
	v_add_f32_e32 v5, v5, v11
	s_waitcnt lgkmcnt(3)
	v_add_f32_e32 v4, v4, v12
	s_brev_b32 s0, 32
	v_lshl_add_u64 v[2:3], s[12:13], 0, v[132:133]
	v_lshl_add_u64 v[136:137], v[0:1], 0, v[128:129]
	v_add_f32_e32 v5, v5, v13
	s_waitcnt lgkmcnt(2)
	v_add_f32_e32 v4, v4, v14
	v_lshl_add_u64 v[2:3], v[2:3], 0, s[10:11]
	v_add_co_u32_e32 v0, vcc, s0, v136
	v_add_f32_e32 v5, v5, v15
	s_waitcnt lgkmcnt(1)
	v_add_f32_e32 v4, v4, v16
	v_lshl_add_u64 v[138:139], v[2:3], 0, v[128:129]
	v_addc_co_u32_e32 v1, vcc, 0, v137, vcc
	v_add_f32_e32 v5, v5, v17
	s_waitcnt lgkmcnt(0)
	v_add_f32_e32 v4, v4, v18
	v_add_co_u32_e32 v2, vcc, 0x4000000, v138
	v_add_f32_e32 v5, v5, v19
	s_nop 0
	v_addc_co_u32_e32 v3, vcc, 0, v139, vcc
	s_waitcnt vmcnt(1)
	v_fmac_f32_e32 v4, 0x3f9837f0, v20
	s_waitcnt vmcnt(0)
	v_fmac_f32_e32 v5, 0x3f9837f0, v21
	global_store_dword v[0:1], v4, off sc1
	global_store_dword v[2:3], v5, off sc1
	s_barrier
	s_waitcnt vmcnt(0)
	s_barrier
	s_mov_b64 s[0:1], exec
	v_readlane_b32 s4, v252, 6
	v_readlane_b32 s5, v252, 7
	s_and_b64 s[4:5], s[0:1], s[4:5]
	s_mov_b64 exec, s[4:5]
	s_cbranch_execz .LBB0_1026
	s_mov_b64 s[4:5], exec
	v_mbcnt_lo_u32_b32 v0, s4, 0
	s_nop 0
	s_waitcnt vmcnt(0)
	s_waitcnt vmcnt(0)
	v_mbcnt_hi_u32_b32 v0, s5, v0
	v_cmp_eq_u32_e32 vcc, 0, v0
	s_and_b64 s[6:7], exec, vcc
	s_mov_b64 exec, s[6:7]
	s_cbranch_execz .LBB0_1026
	s_lshl_b32 s6, s2, 2
	s_andn2_b32 s6, s6, 63
	s_ashr_i32 s7, s6, 31
	s_lshl_b64 s[6:7], s[6:7], 2
	s_add_u32 s6, s3, s6
	s_addc_u32 s7, s33, s7
	s_bcnt1_i32_b64 s4, s[4:5]
	v_mov_b32_e32 v0, 0
	v_mov_b32_e32 v1, s4
	global_atomic_add v0, v1, s[6:7]

; __device__ __forceinline__ unsigned xb_ld(unsigned* p)              { return __hip_atomic_load(p, __ATOMIC_RELAXED, __HIP_MEMORY_SCOPE_AGENT); }
; #define XB_SPIN(cond, bar) do { unsigned _sp = 0; while (cond) { __builtin_amdgcn_s_sleep(1); \
;     if ((++_sp & 255u) == 0u) { if (xb_ld(&(bar)[XB_TMO])) break; if (_sp > XB_SPIN_CAP) { atomicAdd(&(bar)[XB_TMO], 1u); break; } } } } while (0)
; __device__ __forceinline__ void sample_rows_ln(unsigned* cnt_s, unsigned* bar, const float* pre, const float* gam, const float* bet, float* of32, bfu* obf, int bid) {
;     if (bid >= 32) return;
;     if (threadIdx.x == 0) {
;         unsigned* c = cnt_s + (bid >> 1) * 64;
;         XB_SPIN(xb_ld(c) < 16u, bar);
;         __builtin_amdgcn_fence(__ATOMIC_ACQUIRE, "agent");
;         asm volatile("s_waitcnt vmcnt(0)" ::: "memory");
;     }
.LBB0_1070:
	v_readlane_b32 s8, v252, 1
	v_readlane_b32 s9, v252, 2
	s_cmp_lt_i32 s2, 32
	s_mov_b64 s[6:7], s[8:9]
	s_cselect_b64 s[18:19], -1, 0
	s_cmp_gt_i32 s2, 31
	s_cbranch_scc1 .LBB0_1087
	s_load_dwordx2 s[0:1], s[6:7], 0x78
	s_load_dwordx2 s[4:5], s[8:9], 0x80
	s_mov_b64 s[6:7], exec
	v_readlane_b32 s8, v252, 6
	v_readlane_b32 s9, v252, 7
	s_and_b64 s[8:9], s[6:7], s[8:9]
	s_mov_b64 exec, s[8:9]
	s_cbranch_execz .LBB0_1086
	buffer_inv sc1
	s_lshl_b32 s8, s2, 5
	s_andn2_b32 s8, s8, 63
	s_ashr_i32 s9, s8, 31
	s_lshl_b64 s[8:9], s[8:9], 2
	s_add_u32 s20, s3, s8
	s_addc_u32 s21, s33, s9
	v_mov_b32_e32 v0, 0
	global_load_dword v1, v0, s[20:21] sc1
	s_waitcnt vmcnt(0)
	v_cmp_lt_u32_e32 vcc, 15, v1
	s_cbranch_vccnz .LBB0_1085
	s_add_u32 s8, s66, 0x38a00200
	s_addc_u32 s9, s67, 0
	s_mov_b32 s3, 1
	s_branch .LBB0_1075

; __device__ __forceinline__ unsigned xb_ld(unsigned* p)              { return __hip_atomic_load(p, __ATOMIC_RELAXED, __HIP_MEMORY_SCOPE_AGENT); }
; #define XB_SPIN(cond, bar) do { unsigned _sp = 0; while (cond) { __builtin_amdgcn_s_sleep(1); \
;     if ((++_sp & 255u) == 0u) { if (xb_ld(&(bar)[XB_TMO])) break; if (_sp > XB_SPIN_CAP) { atomicAdd(&(bar)[XB_TMO], 1u); break; } } } } while (0)
; __device__ __forceinline__ void sample_rows_ln(unsigned* cnt_s, unsigned* bar, const float* pre, const float* gam, const float* bet, float* of32, bfu* obf, int bid) {
;     ...
;         XB_SPIN(xb_ld(c) < 16u, bar);
;         __builtin_amdgcn_fence(__ATOMIC_ACQUIRE, "agent");
;         asm volatile("s_waitcnt vmcnt(0)" ::: "memory");
.LBB0_1085:
	s_waitcnt vmcnt(0) lgkmcnt(0)
	s_nop 0
	s_waitcnt vmcnt(0)

; __device__ __forceinline__ unsigned xb_ld(unsigned* p)              { return __hip_atomic_load(p, __ATOMIC_RELAXED, __HIP_MEMORY_SCOPE_AGENT); }
; __device__ __forceinline__ void xcd_barrier_complete(unsigned* bar, unsigned x, unsigned& nloc, unsigned& nx) {
;     const unsigned G = gridDim.x * gridDim.y * gridDim.z;
;     unsigned sum, cnt, mine, sp = 0u;
;     for (;;) {
;         sum = 0u; cnt = 0u; mine = 0u;
; #pragma unroll
;         for (unsigned j = 0; j < 16; ++j) { const unsigned c = xb_ld(&bar[XB_XCNT(j)]); sum += c; cnt += (c > 0u) ? 1u : 0u; mine = (j == x) ? c : mine; }
; __device__ __forceinline__ void xcd_barrier(const XcdBarrier& b) {
;     asm volatile("s_waitcnt vmcnt(0)" ::: "memory");
;     __syncthreads();
;     if (threadIdx.x == 0) {
;         unsigned* bar = b.bar;
;         __builtin_amdgcn_s_waitcnt(0);
;         unsigned nloc = b.st[0], nx = b.st[1];
;         if (nloc == 0u) { xcd_barrier_complete(bar, b.x, nloc, nx); b.st[0] = nloc; b.st[1] = nx; }
.LBB0_1087:
	s_waitcnt vmcnt(0)
	s_mov_b64 s[0:1], 0x4000000
	s_barrier
	s_mov_b64 s[4:5], exec
	v_readlane_b32 s6, v252, 6
	v_readlane_b32 s7, v252, 7
	s_and_b64 s[6:7], s[4:5], s[6:7]
	s_mov_b64 exec, s[6:7]
	s_cbranch_execz .LBB0_1139
	s_add_i32 s3, 0, 0x23fc0
	v_mov_b32_e32 v0, s3
	s_waitcnt vmcnt(0) expcnt(0) lgkmcnt(0)
	buffer_inv sc1
	ds_read_b32 v2, v0
	s_add_i32 s3, 0, 0x23fc4
	v_mov_b32_e32 v0, s3
	ds_read_b32 v0, v0
	s_waitcnt lgkmcnt(1)
	v_cmp_ne_u32_e32 vcc, 0, v2
	s_cbranch_vccnz .LBB0_1103
	v_readlane_b32 s3, v252, 0
	s_mul_i32 s3, s93, s3
	s_lshl_b32 s3, s3, 8
	s_add_u32 s6, s66, 0x38a00200
	s_addc_u32 s7, s67, 0
	s_add_u32 s8, s66, 0x38a00400
	s_addc_u32 s9, s67, 0
	s_add_u32 s20, s66, 0x38a00500
	s_addc_u32 s21, s67, 0
	s_add_u32 s22, s66, 0x38a00600
	s_addc_u32 s23, s67, 0
	s_add_u32 s24, s66, 0x38a00700
	s_addc_u32 s25, s67, 0
	s_add_u32 s26, s66, 0x38a00800
	s_addc_u32 s27, s67, 0
	s_add_u32 s28, s66, 0x38a00900
	s_addc_u32 s29, s67, 0
	s_add_u32 s30, s66, 0x38a00a00
	s_addc_u32 s31, s67, 0
	s_add_u32 s34, s66, 0x38a00b00
	s_addc_u32 s35, s67, 0
	s_add_u32 s36, s66, 0x38a00c00
	s_addc_u32 s37, s67, 0
	s_add_u32 s38, s66, 0x38a00d00
	s_addc_u32 s39, s67, 0
	s_add_u32 s40, s66, 0x38a00e00
	s_addc_u32 s41, s67, 0
	s_add_u32 s42, s66, 0x38a00f00
	s_addc_u32 s43, s67, 0
	s_add_u32 s44, s66, 0x38a01000
	s_addc_u32 s45, s67, 0
	s_add_u32 s46, s66, 0x38a01100
	s_addc_u32 s47, s67, 0
	s_add_u32 s48, s66, 0x38a01200
	s_addc_u32 s49, s67, 0
	s_add_u32 s50, s66, 0x38a01300
	s_addc_u32 s51, s67, 0
	s_mov_b32 s11, 1
	v_mov_b32_e32 v16, 0
	s_branch .LBB0_1091

; __device__ __forceinline__ unsigned xb_ld(unsigned* p)              { return __hip_atomic_load(p, __ATOMIC_RELAXED, __HIP_MEMORY_SCOPE_AGENT); }
; #define XB_SPIN(cond, bar) do { unsigned _sp = 0; while (cond) { __builtin_amdgcn_s_sleep(1); \
;     if ((++_sp & 255u) == 0u) { if (xb_ld(&(bar)[XB_TMO])) break; if (_sp > XB_SPIN_CAP) { atomicAdd(&(bar)[XB_TMO], 1u); break; } } } } while (0)
; __device__ __forceinline__ void xcd_barrier(const XcdBarrier& b) {
;     ...
;         } else {
;             XB_SPIN(xb_ld(&bar[XB_XGEN(b.x)]) == gen, bar);
;             __builtin_amdgcn_fence(__ATOMIC_ACQUIRE, "agent");
;             asm volatile("s_waitcnt vmcnt(0)" ::: "memory");
.LBB0_1118:
	s_or_b64 exec, exec, s[20:21]
	s_waitcnt vmcnt(0)
	s_nop 0
	s_waitcnt vmcnt(0)

; __device__ __forceinline__ unsigned xb_ld(unsigned* p)              { return __hip_atomic_load(p, __ATOMIC_RELAXED, __HIP_MEMORY_SCOPE_AGENT); }
; __device__ __forceinline__ unsigned xb_add(unsigned* p, unsigned v) { return __hip_atomic_fetch_add(p, v, __ATOMIC_RELAXED, __HIP_MEMORY_SCOPE_AGENT); }
; #define XB_SPIN(cond, bar) do { unsigned _sp = 0; while (cond) { __builtin_amdgcn_s_sleep(1); \
;     if ((++_sp & 255u) == 0u) { if (xb_ld(&(bar)[XB_TMO])) break; if (_sp > XB_SPIN_CAP) { atomicAdd(&(bar)[XB_TMO], 1u); break; } } } } while (0)
; __device__ __forceinline__ void xcd_barrier(const XcdBarrier& b) {
;     ...
;             else XB_SPIN(xb_ld(&bar[XB_TOPGEN]) == tg, bar);
;             __builtin_amdgcn_fence(__ATOMIC_ACQUIRE, "agent");
;             xb_add(&bar[XB_XGEN(b.x)], 1u);
.LBB0_1136:
	s_or_b64 exec, exec, s[8:9]
	s_mov_b64 s[8:9], exec
	v_mbcnt_lo_u32_b32 v0, s8, 0
	v_mbcnt_hi_u32_b32 v0, s9, v0
	v_cmp_eq_u32_e32 vcc, 0, v0
	s_waitcnt vmcnt(0)
	s_nop 0
	s_and_saveexec_b64 s[20:21], vcc
	s_cbranch_execz .LBB0_1138
	s_bcnt1_i32_b64 s3, s[8:9]
	v_mov_b32_e32 v0, 0x2000
	v_mov_b32_e32 v1, s3
	global_atomic_add v0, v1, s[6:7] offset:1024

; __device__ __forceinline__ unsigned xb_ld(unsigned* p)              { return __hip_atomic_load(p, __ATOMIC_RELAXED, __HIP_MEMORY_SCOPE_AGENT); }
; __device__ __forceinline__ void xcd_barrier_complete(unsigned* bar, unsigned x, unsigned& nloc, unsigned& nx) {
;     const unsigned G = gridDim.x * gridDim.y * gridDim.z;
;     unsigned sum, cnt, mine, sp = 0u;
;     for (;;) {
;         sum = 0u; cnt = 0u; mine = 0u;
; #pragma unroll
;         for (unsigned j = 0; j < 16; ++j) { const unsigned c = xb_ld(&bar[XB_XCNT(j)]); sum += c; cnt += (c > 0u) ? 1u : 0u; mine = (j == x) ? c : mine; }
; __device__ __forceinline__ void xcd_barrier(const XcdBarrier& b) {
;     asm volatile("s_waitcnt vmcnt(0)" ::: "memory");
;     __syncthreads();
;     if (threadIdx.x == 0) {
;         unsigned* bar = b.bar;
;         __builtin_amdgcn_s_waitcnt(0);
;         unsigned nloc = b.st[0], nx = b.st[1];
;         if (nloc == 0u) { xcd_barrier_complete(bar, b.x, nloc, nx); b.st[0] = nloc; b.st[1] = nx; }
.LBB0_1174:
	s_waitcnt vmcnt(0)
	s_waitcnt vmcnt(0)
	s_barrier
	s_mov_b64 s[0:1], exec
	v_readlane_b32 s4, v252, 6
	v_readlane_b32 s5, v252, 7
	s_and_b64 s[4:5], s[0:1], s[4:5]
	s_mov_b64 exec, s[4:5]
	s_cbranch_execz .LBB0_1226
	s_add_i32 s3, 0, 0x23fc0
	v_mov_b32_e32 v0, s3
	s_waitcnt vmcnt(0) expcnt(0) lgkmcnt(0)
	buffer_inv sc1
	ds_read_b32 v2, v0
	s_add_i32 s3, 0, 0x23fc4
	v_mov_b32_e32 v0, s3
	ds_read_b32 v0, v0
	s_waitcnt lgkmcnt(1)
	v_cmp_ne_u32_e32 vcc, 0, v2
	s_cbranch_vccnz .LBB0_1190
	v_readlane_b32 s3, v252, 0
	s_mul_i32 s3, s93, s3
	s_lshl_b32 s3, s3, 8
	s_add_u32 s4, s66, 0x38a00200
	s_addc_u32 s5, s67, 0
	s_add_u32 s6, s66, 0x38a00400
	s_addc_u32 s7, s67, 0
	s_add_u32 s8, s66, 0x38a00500
	s_addc_u32 s9, s67, 0
	s_add_u32 s22, s66, 0x38a00600
	s_addc_u32 s23, s67, 0
	s_add_u32 s24, s66, 0x38a00700
	s_addc_u32 s25, s67, 0
	s_add_u32 s26, s66, 0x38a00800
	s_addc_u32 s27, s67, 0
	s_add_u32 s28, s66, 0x38a00900
	s_addc_u32 s29, s67, 0
	s_add_u32 s30, s66, 0x38a00a00
	s_addc_u32 s31, s67, 0
	s_add_u32 s34, s66, 0x38a00b00
	s_addc_u32 s35, s67, 0
	s_add_u32 s36, s66, 0x38a00c00
	s_addc_u32 s37, s67, 0
	s_add_u32 s38, s66, 0x38a00d00
	s_addc_u32 s39, s67, 0
	s_add_u32 s40, s66, 0x38a00e00
	s_addc_u32 s41, s67, 0
	s_add_u32 s42, s66, 0x38a00f00
	s_addc_u32 s43, s67, 0
	s_add_u32 s44, s66, 0x38a01000
	s_addc_u32 s45, s67, 0
	s_add_u32 s46, s66, 0x38a01100
	s_addc_u32 s47, s67, 0
	s_add_u32 s48, s66, 0x38a01200
	s_addc_u32 s49, s67, 0
	s_add_u32 s50, s66, 0x38a01300
	s_addc_u32 s51, s67, 0
	s_mov_b32 s11, 1
	v_mov_b32_e32 v16, 0
	s_branch .LBB0_1178

; #define MFMA16(a, b, c) __builtin_amdgcn_mfma_f32_16x16x32_bf16((a), (b), (c), 0, 0, 0)
; template <int K>
; __device__ __forceinline__ void skinny_sample_gemm(const bfu* __restrict__ A, const bfu* __restrict__ Bt, const float* __restrict__ res, float* __restrict__ pre, float* ldsf, int bid) {
;     const int tid = threadIdx.x, lane = tid & 63, wave = __builtin_amdgcn_readfirstlane(tid >> 6), l15 = lane & 15, quad = lane >> 4;
;     const int rg = bid >> 4, cg = bid & 15;
;     constexpr int KW = K / 8, NS = KW / 32;
;     const bfu* ap = A + (size_t)(MP + rg * 16 + l15) * K + wave * KW + quad * 8;
;     const bfu* bp = Bt + (size_t)(cg * 64 + l15) * K + wave * KW + quad * 8;
;     f32x4 acc[4];
; #pragma unroll
;     for (int nt = 0; nt < 4; ++nt) acc[nt] = (f32x4){0.f, 0.f, 0.f, 0.f};
; #pragma unroll
;     for (int ks = 0; ks < NS; ++ks) {
;         const bf16x8 af = ld8g(ap + ks * 32);
; #pragma unroll
;         for (int nt = 0; nt < 4; ++nt) acc[nt] = MFMA16(af, ld8g(bp + (size_t)nt * 16 * K + ks * 32), acc[nt]);
;     }
.LBB0_1226:
	s_or_b64 exec, exec, s[0:1]
	s_add_u32 s24, s66, 0x1c00000
	v_readfirstlane_b32 s0, v172
	s_addc_u32 s25, s67, 0
	s_lshr_b32 s0, s0, 6
	s_waitcnt lgkmcnt(0)
	v_mul_u32_u24_e32 v0, 0xb00, v187
	s_mul_i32 s4, s0, 0x160
	s_mov_b32 s5, 0
	v_lshlrev_b32_e32 v44, 1, v0
	v_mov_b32_e32 v45, 0
	v_lshl_add_u64 v[4:5], s[24:25], 0, v[44:45]
	s_lshl_b64 s[4:5], s[4:5], 1
	s_movk_i32 s1, 0x1600
	v_mov_b64_e32 v[0:1], s[20:21]
	v_mad_i64_i32 v[0:1], s[6:7], v134, s1, v[0:1]
	v_lshlrev_b32_e32 v44, 1, v195
	v_lshl_add_u64 v[4:5], v[4:5], 0, s[4:5]
	v_lshl_add_u64 v[0:1], v[0:1], 0, s[4:5]
	v_lshl_add_u64 v[48:49], v[4:5], 0, v[44:45]
	s_mov_b32 s1, 0x16000
	v_lshl_add_u64 v[46:47], v[0:1], 0, v[44:45]
	v_add_co_u32_e32 v50, vcc, s1, v48
	s_barrier
	global_load_dwordx4 v[0:3], v[46:47], off
	global_load_dwordx4 v[4:7], v[48:49], off
	s_mov_b32 s3, 0x2c000
	v_addc_co_u32_e32 v51, vcc, 0, v49, vcc
	v_add_co_u32_e32 v52, vcc, s3, v48
	s_mov_b32 s1, 0x42000
	s_nop 0
	v_addc_co_u32_e32 v53, vcc, 0, v49, vcc
	v_add_co_u32_e32 v54, vcc, s1, v48
	global_load_dwordx4 v[8:11], v[50:51], off
	global_load_dwordx4 v[12:15], v[46:47], off offset:64
	global_load_dwordx4 v[16:19], v[46:47], off offset:640
	global_load_dwordx4 v[20:23], v[52:53], off
	v_addc_co_u32_e32 v55, vcc, 0, v49, vcc
	global_load_dwordx4 v[24:27], v[50:51], off offset:64
	global_load_dwordx4 v[28:31], v[50:51], off offset:640
	global_load_dwordx4 v[32:35], v[54:55], off
	global_load_dwordx4 v[36:39], v[54:55], off offset:64
	s_lshl_b32 s0, s0, 12
	s_add_i32 s0, s0, 0
	v_mov_b32_e32 v129, v45
	s_waitcnt vmcnt(8)
	v_mfma_f32_16x16x32_bf16 v[4:7], v[0:3], v[4:7], 0
	s_waitcnt vmcnt(7)
	v_mfma_f32_16x16x32_bf16 v[8:11], v[0:3], v[8:11], 0
	s_waitcnt vmcnt(4)
	v_mfma_f32_16x16x32_bf16 v[20:23], v[0:3], v[20:23], 0
	s_waitcnt vmcnt(1)
	v_mfma_f32_16x16x32_bf16 v[0:3], v[0:3], v[32:35], 0
	global_load_dwordx4 v[32:35], v[48:49], off offset:64
	global_load_dwordx4 v[40:43], v[48:49], off offset:128
	v_mfma_f32_16x16x32_bf16 v[8:11], v[12:15], v[24:27], v[8:11]
	s_waitcnt vmcnt(2)
	v_mfma_f32_16x16x32_bf16 v[0:3], v[12:15], v[36:39], v[0:3]
	s_waitcnt vmcnt(1)
	v_mfma_f32_16x16x32_bf16 v[4:7], v[12:15], v[32:35], v[4:7]
	global_load_dwordx4 v[24:27], v[52:53], off offset:64
	global_load_dwordx4 v[32:35], v[52:53], off offset:128
	s_waitcnt vmcnt(1)
	v_mfma_f32_16x16x32_bf16 v[20:23], v[12:15], v[24:27], v[20:23]
	global_load_dwordx4 v[12:15], v[46:47], off offset:128
	global_load_dwordx4 v[24:27], v[46:47], off offset:192
	s_waitcnt vmcnt(1)
	v_mfma_f32_16x16x32_bf16 v[4:7], v[12:15], v[40:43], v[4:7]
	global_load_dwordx4 v[36:39], v[50:51], off offset:128
	global_load_dwordx4 v[40:43], v[50:51], off offset:192
	v_mfma_f32_16x16x32_bf16 v[20:23], v[12:15], v[32:35], v[20:23]
	s_waitcnt vmcnt(1)
	v_mfma_f32_16x16x32_bf16 v[8:11], v[12:15], v[36:39], v[8:11]
	global_load_dwordx4 v[32:35], v[54:55], off offset:128
	global_load_dwordx4 v[36:39], v[54:55], off offset:192
	s_waitcnt vmcnt(2)
	v_mfma_f32_16x16x32_bf16 v[8:11], v[24:27], v[40:43], v[8:11]
	s_waitcnt vmcnt(1)
	v_mfma_f32_16x16x32_bf16 v[0:3], v[12:15], v[32:35], v[0:3]
	global_load_dwordx4 v[12:15], v[48:49], off offset:192
	global_load_dwordx4 v[32:35], v[48:49], off offset:256
	s_waitcnt vmcnt(2)
	v_mfma_f32_16x16x32_bf16 v[0:3], v[24:27], v[36:39], v[0:3]
	s_waitcnt vmcnt(1)
	v_mfma_f32_16x16x32_bf16 v[4:7], v[24:27], v[12:15], v[4:7]
	global_load_dwordx4 v[12:15], v[52:53], off offset:192
	global_load_dwordx4 v[40:43], v[52:53], off offset:256
	s_waitcnt vmcnt(1)
	v_mfma_f32_16x16x32_bf16 v[12:15], v[24:27], v[12:15], v[20:23]
	s_nop 2
	global_load_dwordx4 v[20:23], v[46:47], off offset:256
	global_load_dwordx4 v[24:27], v[46:47], off offset:320
	s_waitcnt vmcnt(1)
	v_mfma_f32_16x16x32_bf16 v[4:7], v[20:23], v[32:35], v[4:7]
	global_load_dwordx4 v[32:35], v[50:51], off offset:256
	global_load_dwordx4 v[36:39], v[50:51], off offset:320
	v_mfma_f32_16x16x32_bf16 v[12:15], v[20:23], v[40:43], v[12:15]
	s_waitcnt vmcnt(1)
	v_mfma_f32_16x16x32_bf16 v[8:11], v[20:23], v[32:35], v[8:11]
	global_load_dwordx4 v[32:35], v[54:55], off offset:256
	global_load_dwordx4 v[40:43], v[54:55], off offset:320
	s_waitcnt vmcnt(2)
	v_mfma_f32_16x16x32_bf16 v[8:11], v[24:27], v[36:39], v[8:11]
	s_waitcnt vmcnt(1)
	v_mfma_f32_16x16x32_bf16 v[0:3], v[20:23], v[32:35], v[0:3]
	global_load_dwordx4 v[20:23], v[48:49], off offset:320
	global_load_dwordx4 v[32:35], v[48:49], off offset:384
	s_waitcnt vmcnt(2)
	v_mfma_f32_16x16x32_bf16 v[0:3], v[24:27], v[40:43], v[0:3]
	s_waitcnt vmcnt(1)
	v_mfma_f32_16x16x32_bf16 v[4:7], v[24:27], v[20:23], v[4:7]
	global_load_dwordx4 v[20:23], v[52:53], off offset:320
	global_load_dwordx4 v[36:39], v[52:53], off offset:384
	s_waitcnt vmcnt(1)
	v_mfma_f32_16x16x32_bf16 v[12:15], v[24:27], v[20:23], v[12:15]
	global_load_dwordx4 v[20:23], v[46:47], off offset:384
	global_load_dwordx4 v[24:27], v[46:47], off offset:448
	s_waitcnt vmcnt(1)
	v_mfma_f32_16x16x32_bf16 v[4:7], v[20:23], v[32:35], v[4:7]
	global_load_dwordx4 v[32:35], v[50:51], off offset:384
	global_load_dwordx4 v[40:43], v[50:51], off offset:448
	v_mfma_f32_16x16x32_bf16 v[12:15], v[20:23], v[36:39], v[12:15]
	s_waitcnt vmcnt(1)
; __device__ __forceinline__ unsigned xb_add(unsigned* p, unsigned v) { return __hip_atomic_fetch_add(p, v, __ATOMIC_RELAXED, __HIP_MEMORY_SCOPE_AGENT); }
; #define MFMA16(a, b, c) __builtin_amdgcn_mfma_f32_16x16x32_bf16((a), (b), (c), 0, 0, 0)
; template <int K>
; __device__ __forceinline__ void skinny_sample_gemm(const bfu* __restrict__ A, const bfu* __restrict__ Bt, const float* __restrict__ res, float* __restrict__ pre, float* ldsf, int bid) {
;     ...
; #pragma unroll
;     for (int ks = 0; ks < NS; ++ks) {
;         const bf16x8 af = ld8g(ap + ks * 32);
; #pragma unroll
;         for (int nt = 0; nt < 4; ++nt) acc[nt] = MFMA16(af, ld8g(bp + (size_t)nt * 16 * K + ks * 32), acc[nt]);
;     }
; #pragma unroll
;     for (int nt = 0; nt < 4; ++nt)
; #pragma unroll
;         for (int j = 0; j < 4; ++j) ldsf[wave * 1024 + (quad * 4 + j) * 64 + nt * 16 + l15] = acc[nt][j];
;     __syncthreads();
; #pragma unroll
;     for (int i = 0; i < 2; ++i) {
;         const int e = tid + 512 * i, r = e >> 6, c = e & 63;
;         float v = 0.f;
; #pragma unroll
;         for (int w = 0; w < 8; ++w) v += ldsf[w * 1024 + e];
;         const size_t row = (size_t)(rg * 16 + r);
;         pre[(MP + row) * 1024 + cg * 64 + c] = v + ALPHA * res[row * 1024 + cg * 64 + c];
;     }
;     __syncthreads();
; }
; __device__ __forceinline__ void sample_rows_publish(unsigned* cnt_s, int bid) {
;     asm volatile("s_waitcnt vmcnt(0)" ::: "memory");
;     __syncthreads();
;     if (threadIdx.x == 0) { __builtin_amdgcn_fence(__ATOMIC_RELEASE, "agent"); asm volatile("s_waitcnt vmcnt(0)" ::: "memory"); xb_add(cnt_s + (bid >> 4) * 64, 1u); }
; }
	v_mfma_f32_16x16x32_bf16 v[8:11], v[20:23], v[32:35], v[8:11]
	global_load_dwordx4 v[32:35], v[54:55], off offset:384
	global_load_dwordx4 v[36:39], v[54:55], off offset:448
	s_waitcnt vmcnt(2)
	v_mfma_f32_16x16x32_bf16 v[8:11], v[24:27], v[40:43], v[8:11]
	s_waitcnt vmcnt(1)
	v_mfma_f32_16x16x32_bf16 v[0:3], v[20:23], v[32:35], v[0:3]
	global_load_dwordx4 v[20:23], v[48:49], off offset:448
	global_load_dwordx4 v[32:35], v[48:49], off offset:512
	s_waitcnt vmcnt(2)
	v_mfma_f32_16x16x32_bf16 v[0:3], v[24:27], v[36:39], v[0:3]
	s_waitcnt vmcnt(1)
	v_mfma_f32_16x16x32_bf16 v[4:7], v[24:27], v[20:23], v[4:7]
	global_load_dwordx4 v[20:23], v[52:53], off offset:448
	global_load_dwordx4 v[40:43], v[52:53], off offset:512
	s_waitcnt vmcnt(1)
	v_mfma_f32_16x16x32_bf16 v[12:15], v[24:27], v[20:23], v[12:15]
	global_load_dwordx4 v[20:23], v[46:47], off offset:512
	global_load_dwordx4 v[24:27], v[46:47], off offset:576
	s_waitcnt vmcnt(1)
	v_mfma_f32_16x16x32_bf16 v[4:7], v[20:23], v[32:35], v[4:7]
	global_load_dwordx4 v[32:35], v[50:51], off offset:512
	global_load_dwordx4 v[36:39], v[50:51], off offset:576
	v_mfma_f32_16x16x32_bf16 v[12:15], v[20:23], v[40:43], v[12:15]
	s_waitcnt vmcnt(1)
	v_mfma_f32_16x16x32_bf16 v[8:11], v[20:23], v[32:35], v[8:11]
	global_load_dwordx4 v[32:35], v[54:55], off offset:512
	global_load_dwordx4 v[40:43], v[54:55], off offset:576
	s_waitcnt vmcnt(2)
	v_mfma_f32_16x16x32_bf16 v[8:11], v[24:27], v[36:39], v[8:11]
	v_mfma_f32_16x16x32_bf16 v[8:11], v[16:19], v[28:31], v[8:11]
	s_waitcnt vmcnt(1)
	v_mfma_f32_16x16x32_bf16 v[0:3], v[20:23], v[32:35], v[0:3]
	global_load_dwordx4 v[20:23], v[48:49], off offset:576
	global_load_dwordx4 v[32:35], v[48:49], off offset:640
	s_waitcnt vmcnt(2)
	v_mfma_f32_16x16x32_bf16 v[0:3], v[24:27], v[40:43], v[0:3]
	s_waitcnt vmcnt(1)
	v_mfma_f32_16x16x32_bf16 v[4:7], v[24:27], v[20:23], v[4:7]
	global_load_dwordx4 v[20:23], v[52:53], off offset:576
	global_load_dwordx4 v[36:39], v[52:53], off offset:640
	s_waitcnt vmcnt(2)
	v_mfma_f32_16x16x32_bf16 v[4:7], v[16:19], v[32:35], v[4:7]
	s_waitcnt vmcnt(1)
	v_mfma_f32_16x16x32_bf16 v[12:15], v[24:27], v[20:23], v[12:15]
	global_load_dwordx4 v[20:23], v[54:55], off offset:640
	v_add3_u32 v24, s0, v135, v186
	s_add_u32 s0, s66, s10
	s_waitcnt vmcnt(1)
	v_mfma_f32_16x16x32_bf16 v[12:15], v[16:19], v[36:39], v[12:15]
	s_addc_u32 s1, s67, 0
	ds_write2_b32 v24, v4, v8 offset1:16
	ds_write2_b32 v24, v5, v9 offset0:64 offset1:80
	ds_write2_b32 v24, v6, v10 offset0:128 offset1:144
	ds_write2_b32 v24, v7, v11 offset0:192 offset1:208
	s_add_u32 s3, s66, 0x38a0d000
	s_addc_u32 s33, s67, 0
	s_waitcnt vmcnt(0)
	v_mfma_f32_16x16x32_bf16 v[0:3], v[16:19], v[20:23], v[0:3]
	s_nop 7
	ds_write2_b32 v24, v12, v0 offset0:32 offset1:48
	ds_write2_b32 v24, v13, v1 offset0:96 offset1:112
	ds_write2_b32 v24, v14, v2 offset0:160 offset1:176
	ds_write2_b32 v24, v15, v3 offset0:224 offset1:240
	v_lshl_add_u64 v[0:1], s[0:1], 0, v[128:129]
	s_mov_b64 s[0:1], 0x30e00000
	v_lshl_add_u64 v[0:1], v[0:1], 0, s[0:1]
	v_lshl_add_u64 v[2:3], v[0:1], 0, v[130:131]
	s_waitcnt lgkmcnt(0)
	s_barrier
	v_lshl_add_u64 v[0:1], v[0:1], 0, v[132:133]
	global_load_dword v16, v[2:3], off
	global_load_dword v17, v[0:1], off
	ds_read2st64_b32 v[0:1], v173 offset1:8
	ds_read2st64_b32 v[2:3], v173 offset0:16 offset1:24
	ds_read2st64_b32 v[4:5], v173 offset0:32 offset1:40
	ds_read2st64_b32 v[6:7], v173 offset0:48 offset1:56
	ds_read2st64_b32 v[8:9], v173 offset0:64 offset1:72
	ds_read2st64_b32 v[10:11], v173 offset0:80 offset1:88
	ds_read2st64_b32 v[12:13], v173 offset0:96 offset1:104
	ds_read2st64_b32 v[14:15], v173 offset0:112 offset1:120
	s_waitcnt lgkmcnt(7)
	v_add_f32_e32 v0, 0, v0
	v_add_f32_e32 v1, 0, v1
	s_waitcnt lgkmcnt(6)
	v_add_f32_e32 v0, v0, v2
	v_add_f32_e32 v1, v1, v3
	s_waitcnt lgkmcnt(5)
	v_add_f32_e32 v0, v0, v4
	v_add_f32_e32 v1, v1, v5
	s_waitcnt lgkmcnt(4)
	v_add_f32_e32 v0, v0, v6
	v_add_f32_e32 v1, v1, v7
	s_waitcnt lgkmcnt(3)
	v_add_f32_e32 v0, v0, v8
	v_add_f32_e32 v1, v1, v9
	s_waitcnt lgkmcnt(2)
	v_add_f32_e32 v0, v0, v10
	v_add_f32_e32 v1, v1, v11
	s_waitcnt lgkmcnt(1)
	v_add_f32_e32 v0, v0, v12
	v_add_f32_e32 v1, v1, v13
	s_waitcnt lgkmcnt(0)
	v_add_f32_e32 v0, v0, v14
	v_add_f32_e32 v1, v1, v15
	s_waitcnt vmcnt(1)
	v_fmac_f32_e32 v0, 0x3f9837f0, v16
	s_waitcnt vmcnt(0)
	v_fmac_f32_e32 v1, 0x3f9837f0, v17
	global_store_dword v[136:137], v0, off sc1
	global_store_dword v[138:139], v1, off sc1
	s_barrier
	s_waitcnt vmcnt(0)
	s_barrier
	s_mov_b64 s[0:1], exec
	v_readlane_b32 s4, v252, 6
	v_readlane_b32 s5, v252, 7
	s_and_b64 s[4:5], s[0:1], s[4:5]
	s_mov_b64 exec, s[4:5]
	s_cbranch_execz .LBB0_1229
	s_mov_b64 s[4:5], exec
	v_mbcnt_lo_u32_b32 v0, s4, 0
	s_nop 0
	s_waitcnt vmcnt(0)
	s_waitcnt vmcnt(0)
	v_mbcnt_hi_u32_b32 v0, s5, v0
	v_cmp_eq_u32_e32 vcc, 0, v0
	s_and_b64 s[6:7], exec, vcc
	s_mov_b64 exec, s[6:7]
	s_cbranch_execz .LBB0_1229
	s_lshl_b32 s6, s2, 2
	s_andn2_b32 s6, s6, 63
	s_ashr_i32 s7, s6, 31
	s_lshl_b64 s[6:7], s[6:7], 2
	s_add_u32 s6, s3, s6
	s_addc_u32 s7, s33, s7
	s_bcnt1_i32_b64 s4, s[4:5]
	v_mov_b32_e32 v0, 0
	v_mov_b32_e32 v1, s4
	global_atomic_add v0, v1, s[6:7]

; __device__ __forceinline__ unsigned xb_ld(unsigned* p)              { return __hip_atomic_load(p, __ATOMIC_RELAXED, __HIP_MEMORY_SCOPE_AGENT); }
; #define XB_SPIN(cond, bar) do { unsigned _sp = 0; while (cond) { __builtin_amdgcn_s_sleep(1); \
;     if ((++_sp & 255u) == 0u) { if (xb_ld(&(bar)[XB_TMO])) break; if (_sp > XB_SPIN_CAP) { atomicAdd(&(bar)[XB_TMO], 1u); break; } } } } while (0)
; __device__ __forceinline__ void sample_rows_ln(unsigned* cnt_s, unsigned* bar, const float* pre, const float* gam, const float* bet, float* of32, bfu* obf, int bid) {
;     if (bid >= 32) return;
;     if (threadIdx.x == 0) {
;         unsigned* c = cnt_s + (bid >> 1) * 64;
;         XB_SPIN(xb_ld(c) < 16u, bar);
;         __builtin_amdgcn_fence(__ATOMIC_ACQUIRE, "agent");
;         asm volatile("s_waitcnt vmcnt(0)" ::: "memory");
;     }
.LBB0_1278:
	v_readlane_b32 s0, v252, 1
	v_readlane_b32 s1, v252, 2
	s_mov_b64 s[8:9], s[0:1]
	s_mov_b64 s[10:11], s[0:1]
	s_andn2_b64 vcc, exec, s[18:19]
	s_cbranch_vccnz .LBB0_1296
	s_mov_b64 s[6:7], s[0:1]
	s_load_dwordx2 s[4:5], s[8:9], 0xa0
	s_load_dwordx2 s[0:1], s[10:11], 0xa8
	s_mov_b64 s[14:15], s[6:7]
	s_load_dwordx2 s[6:7], s[6:7], 0xb0
	s_mov_b64 s[8:9], exec
	v_readlane_b32 s10, v252, 6
	v_readlane_b32 s11, v252, 7
	s_and_b64 s[10:11], s[8:9], s[10:11]
	s_mov_b64 exec, s[10:11]
	s_cbranch_execz .LBB0_1294
	buffer_inv sc1
	s_lshl_b32 s2, s2, 5
	s_and_b32 s10, s2, 0xffffffc0
	s_ashr_i32 s11, s10, 31
	s_lshl_b64 s[10:11], s[10:11], 2
	s_add_u32 s10, s3, s10
	s_addc_u32 s11, s33, s11
	v_mov_b32_e32 v0, 0
	global_load_dword v1, v0, s[10:11] sc1
	s_waitcnt vmcnt(0)
	v_cmp_lt_u32_e32 vcc, 15, v1
	s_cbranch_vccnz .LBB0_1293
	s_add_u32 s2, s66, 0x38a00200
	s_addc_u32 s3, s67, 0
	s_mov_b32 s20, 1
	s_branch .LBB0_1283
